# pre-MLP rmsnorm fused into the out-proj residual epilogue (bf16(x*gain) + row sum-of-squares partials); 1/rms^2 per row applied in f32 inside the MLP-down residual epilogue as x + s*acc
# speedup vs baseline: 1.0033x; 1.0019x over previous
.LBB0_943:
	s_cmp_le_i32 s58, s40
	s_cselect_b64 s[0:1], -1, 0
	s_and_b64 s[4:5], s[0:1], s[44:45]
	s_andn2_b64 vcc, exec, s[4:5]
	s_cbranch_vccnz .LBB0_947
	s_mov_b32 s4, s80
	v_mbcnt_lo_u32_b32 v0, -1, 0
	v_mbcnt_hi_u32_b32 v0, -1, v0
	s_add_i32 s4, s4, s81
	s_mov_b64 s[6:7], s[56:57]
	s_cmpk_gt_i32 s4, 0x7fff
	s_cbranch_scc1 .LBB0_947
	s_waitcnt vmcnt(0) lgkmcnt(0)
	s_load_dwordx2 s[98:99], s[56:57], 0xd8
	v_lshrrev_b32_e32 v2, 4, v0
	v_and_b32_e32 v3, 15, v0
	v_lshlrev_b32_e32 v4, 11, v2
	v_add_u32_e32 v4, s4, v4
	v_lshlrev_b32_e32 v5, 6, v4
	v_lshl_add_u32 v5, v3, 2, v5
	v_lshlrev_b32_e32 v6, 2, v4
	s_waitcnt lgkmcnt(0)
	s_add_u32 s98, s98, 0x8789000
	s_addc_u32 s99, s99, 0
	global_load_dword v8, v5, s[98:99]
	v_add_u32_e32 v5, 0x80000, v5
	global_load_dword v9, v5, s[98:99]
	v_add_u32_e32 v5, 0x80000, v5
	global_load_dword v10, v5, s[98:99]
	v_add_u32_e32 v5, 0x80000, v5
	global_load_dword v11, v5, s[98:99]
	s_waitcnt vmcnt(0)
	v_lshlrev_b32_e32 v7, 2, v0
	v_xor_b32_e32 v12, 4, v7
	v_xor_b32_e32 v13, 8, v7
	v_xor_b32_e32 v14, 16, v7
	v_xor_b32_e32 v15, 32, v7
	ds_bpermute_b32 v16, v12, v8
	s_waitcnt lgkmcnt(0)
	v_add_f32_e32 v8, v8, v16
	ds_bpermute_b32 v16, v13, v8
	s_waitcnt lgkmcnt(0)
	v_add_f32_e32 v8, v8, v16
	ds_bpermute_b32 v16, v14, v8
	s_waitcnt lgkmcnt(0)
	v_add_f32_e32 v8, v8, v16
	ds_bpermute_b32 v16, v15, v8
	s_waitcnt lgkmcnt(0)
	v_add_f32_e32 v8, v8, v16
	ds_bpermute_b32 v16, v12, v9
	s_waitcnt lgkmcnt(0)
	v_add_f32_e32 v9, v9, v16
	ds_bpermute_b32 v16, v13, v9
	s_waitcnt lgkmcnt(0)
	v_add_f32_e32 v9, v9, v16
	ds_bpermute_b32 v16, v14, v9
	s_waitcnt lgkmcnt(0)
	v_add_f32_e32 v9, v9, v16
	ds_bpermute_b32 v16, v15, v9
	s_waitcnt lgkmcnt(0)
	v_add_f32_e32 v9, v9, v16
	ds_bpermute_b32 v16, v12, v10
	s_waitcnt lgkmcnt(0)
	v_add_f32_e32 v10, v10, v16
	ds_bpermute_b32 v16, v13, v10
	s_waitcnt lgkmcnt(0)
	v_add_f32_e32 v10, v10, v16
	ds_bpermute_b32 v16, v14, v10
	s_waitcnt lgkmcnt(0)
	v_add_f32_e32 v10, v10, v16
	ds_bpermute_b32 v16, v15, v10
	s_waitcnt lgkmcnt(0)
	v_add_f32_e32 v10, v10, v16
	ds_bpermute_b32 v16, v12, v11
	s_waitcnt lgkmcnt(0)
	v_add_f32_e32 v11, v11, v16
	ds_bpermute_b32 v16, v13, v11
	s_waitcnt lgkmcnt(0)
	v_add_f32_e32 v11, v11, v16
	ds_bpermute_b32 v16, v14, v11
	s_waitcnt lgkmcnt(0)
	v_add_f32_e32 v11, v11, v16
	ds_bpermute_b32 v16, v15, v11
	s_waitcnt lgkmcnt(0)
	v_add_f32_e32 v11, v11, v16
	v_mov_b32_e32 v17, 0x358637bd
	v_mov_b32_e32 v18, 0x800000
	s_mov_b32 s100, 0x10001
	s_mov_b32 s101, 0x10001
	v_fmamk_f32 v8, v8, 0x3a800000, v17
	v_cmp_gt_f32_e32 vcc, v18, v8
	v_mul_f32_e32 v16, 0x4b800000, v8
	s_nop 0
	v_cndmask_b32_e32 v8, v8, v16, vcc
	v_rsq_f32_e32 v8, v8
	s_nop 0
	v_mul_f32_e32 v16, 0x45800000, v8
	v_cndmask_b32_e32 v8, v8, v16, vcc
	v_fmamk_f32 v9, v9, 0x3a800000, v17
	v_cmp_gt_f32_e32 vcc, v18, v9
	v_mul_f32_e32 v16, 0x4b800000, v9
	s_nop 0
	v_cndmask_b32_e32 v9, v9, v16, vcc
	v_rsq_f32_e32 v9, v9
	s_nop 0
	v_mul_f32_e32 v16, 0x45800000, v9
	v_cndmask_b32_e32 v9, v9, v16, vcc
	v_fmamk_f32 v10, v10, 0x3a800000, v17
	v_cmp_gt_f32_e32 vcc, v18, v10
	v_mul_f32_e32 v16, 0x4b800000, v10
	s_nop 0
	v_cndmask_b32_e32 v10, v10, v16, vcc
	v_rsq_f32_e32 v10, v10
	s_nop 0
	v_mul_f32_e32 v16, 0x45800000, v10
	v_cndmask_b32_e32 v10, v10, v16, vcc
	v_fmamk_f32 v11, v11, 0x3a800000, v17
	v_cmp_gt_f32_e32 vcc, v18, v11
	v_mul_f32_e32 v16, 0x4b800000, v11
	s_nop 0
	v_cndmask_b32_e32 v11, v11, v16, vcc
	v_rsq_f32_e32 v11, v11
	s_nop 0
	v_mul_f32_e32 v16, 0x45800000, v11
	v_cndmask_b32_e32 v11, v11, v16, vcc
	v_mul_f32_e32 v8, v8, v8
	v_mul_f32_e32 v9, v9, v9
	v_mul_f32_e32 v10, v10, v10
	v_mul_f32_e32 v11, v11, v11
	s_mov_b64 exec, s[100:101]
	v_add_u32_e32 v6, 0x200000, v6
	global_store_dword v6, v8, s[98:99]
	v_add_u32_e32 v6, 0x8000, v6
	global_store_dword v6, v9, s[98:99]
	v_add_u32_e32 v6, 0x8000, v6
	global_store_dword v6, v10, s[98:99]
	v_add_u32_e32 v6, 0x8000, v6
	global_store_dword v6, v11, s[98:99]
	s_mov_b64 exec, -1

.LBB0_1077:
	v_lshl_or_b32 v158, s24, 8, v164
	v_lshl_add_u32 v241, s25, 8, v162
	v_lshlrev_b32_e32 v240, 12, v241
	v_lshl_add_u32 v240, v158, 2, v240
	s_load_dwordx2 s[98:99], s[56:57], 0xd8
	v_lshlrev_b32_e32 v241, 2, v241
	v_readfirstlane_b32 s100, v2
	v_readfirstlane_b32 s101, v3
	s_waitcnt lgkmcnt(0)
	s_add_u32 s98, s98, 0x8989000
	s_addc_u32 s99, s99, 0
	s_nop 4
	v_mov_b32_e32 v158, v240
	global_load_dwordx4 v[166:169], v158, s[100:101]
	global_load_dwordx4 v[170:173], v158, s[100:101] offset:16
	global_load_dwordx4 v[174:177], v158, s[100:101] offset:512
	global_load_dwordx4 v[178:181], v158, s[100:101] offset:528
	v_add_u32_e32 v158, 0x10000, v158
	global_load_dwordx4 v[182:185], v158, s[100:101]
	global_load_dwordx4 v[186:189], v158, s[100:101] offset:16
	global_load_dwordx4 v[190:193], v158, s[100:101] offset:512
	global_load_dwordx4 v[194:197], v158, s[100:101] offset:528
	v_add_u32_e32 v158, 0x10000, v158
	global_load_dwordx4 v[200:203], v158, s[100:101]
	global_load_dwordx4 v[204:207], v158, s[100:101] offset:16
	global_load_dwordx4 v[208:211], v158, s[100:101] offset:512
	global_load_dwordx4 v[212:215], v158, s[100:101] offset:528
	v_add_u32_e32 v158, 0x10000, v158
	global_load_dwordx4 v[216:219], v158, s[100:101]
	global_load_dwordx4 v[220:223], v158, s[100:101] offset:16
	global_load_dwordx4 v[224:227], v158, s[100:101] offset:512
	global_load_dwordx4 v[228:231], v158, s[100:101] offset:528
	global_load_dword v232, v241, s[98:99]
	global_load_dword v234, v241, s[98:99] offset:64
	global_load_dword v236, v241, s[98:99] offset:128
	global_load_dword v238, v241, s[98:99] offset:192
	s_waitcnt vmcnt(0)
	v_pk_fma_f32 v[128:129], v[128:129], v[232:233], v[166:167] op_sel_hi:[1,0,1]
	v_pk_fma_f32 v[130:131], v[130:131], v[232:233], v[168:169] op_sel_hi:[1,0,1]
	v_pk_fma_f32 v[124:125], v[124:125], v[232:233], v[170:171] op_sel_hi:[1,0,1]
	v_pk_fma_f32 v[126:127], v[126:127], v[232:233], v[172:173] op_sel_hi:[1,0,1]
	v_pk_fma_f32 v[112:113], v[112:113], v[232:233], v[174:175] op_sel_hi:[1,0,1]
	v_pk_fma_f32 v[114:115], v[114:115], v[232:233], v[176:177] op_sel_hi:[1,0,1]
	v_pk_fma_f32 v[104:105], v[104:105], v[232:233], v[178:179] op_sel_hi:[1,0,1]
	v_pk_fma_f32 v[106:107], v[106:107], v[232:233], v[180:181] op_sel_hi:[1,0,1]
	v_pk_fma_f32 v[120:121], v[120:121], v[234:235], v[182:183] op_sel_hi:[1,0,1]
	v_pk_fma_f32 v[122:123], v[122:123], v[234:235], v[184:185] op_sel_hi:[1,0,1]
	v_pk_fma_f32 v[116:117], v[116:117], v[234:235], v[186:187] op_sel_hi:[1,0,1]
	v_pk_fma_f32 v[118:119], v[118:119], v[234:235], v[188:189] op_sel_hi:[1,0,1]
	v_pk_fma_f32 v[96:97], v[96:97], v[234:235], v[190:191] op_sel_hi:[1,0,1]
	v_pk_fma_f32 v[98:99], v[98:99], v[234:235], v[192:193] op_sel_hi:[1,0,1]
	v_pk_fma_f32 v[88:89], v[88:89], v[234:235], v[194:195] op_sel_hi:[1,0,1]
	v_pk_fma_f32 v[90:91], v[90:91], v[234:235], v[196:197] op_sel_hi:[1,0,1]
	v_pk_fma_f32 v[108:109], v[108:109], v[236:237], v[200:201] op_sel_hi:[1,0,1]
	v_pk_fma_f32 v[110:111], v[110:111], v[236:237], v[202:203] op_sel_hi:[1,0,1]
	v_pk_fma_f32 v[100:101], v[100:101], v[236:237], v[204:205] op_sel_hi:[1,0,1]
	v_pk_fma_f32 v[102:103], v[102:103], v[236:237], v[206:207] op_sel_hi:[1,0,1]
	v_pk_fma_f32 v[80:81], v[80:81], v[236:237], v[208:209] op_sel_hi:[1,0,1]
	v_pk_fma_f32 v[82:83], v[82:83], v[236:237], v[210:211] op_sel_hi:[1,0,1]
	v_pk_fma_f32 v[76:77], v[76:77], v[236:237], v[212:213] op_sel_hi:[1,0,1]
	v_pk_fma_f32 v[78:79], v[78:79], v[236:237], v[214:215] op_sel_hi:[1,0,1]
	v_pk_fma_f32 v[92:93], v[92:93], v[238:239], v[216:217] op_sel_hi:[1,0,1]
	v_pk_fma_f32 v[94:95], v[94:95], v[238:239], v[218:219] op_sel_hi:[1,0,1]
	v_pk_fma_f32 v[84:85], v[84:85], v[238:239], v[220:221] op_sel_hi:[1,0,1]
	v_pk_fma_f32 v[86:87], v[86:87], v[238:239], v[222:223] op_sel_hi:[1,0,1]
	v_pk_fma_f32 v[72:73], v[72:73], v[238:239], v[224:225] op_sel_hi:[1,0,1]
	v_pk_fma_f32 v[74:75], v[74:75], v[238:239], v[226:227] op_sel_hi:[1,0,1]
	v_pk_fma_f32 v[68:69], v[68:69], v[238:239], v[228:229] op_sel_hi:[1,0,1]
	v_pk_fma_f32 v[70:71], v[70:71], v[238:239], v[230:231] op_sel_hi:[1,0,1]
	v_mov_b32_e32 v158, v240
	global_store_dwordx4 v158, v[128:131], s[100:101]
	global_store_dwordx4 v158, v[124:127], s[100:101] offset:16
	global_store_dwordx4 v158, v[112:115], s[100:101] offset:512
	global_store_dwordx4 v158, v[104:107], s[100:101] offset:528
	v_add_u32_e32 v158, 0x10000, v158
	global_store_dwordx4 v158, v[120:123], s[100:101]
	global_store_dwordx4 v158, v[116:119], s[100:101] offset:16
	global_store_dwordx4 v158, v[96:99], s[100:101] offset:512
	global_store_dwordx4 v158, v[88:91], s[100:101] offset:528
	v_add_u32_e32 v158, 0x10000, v158
	global_store_dwordx4 v158, v[108:111], s[100:101]
	global_store_dwordx4 v158, v[100:103], s[100:101] offset:16
	global_store_dwordx4 v158, v[80:83], s[100:101] offset:512
	global_store_dwordx4 v158, v[76:79], s[100:101] offset:528
	v_add_u32_e32 v158, 0x10000, v158
	global_store_dwordx4 v158, v[92:95], s[100:101]
	global_store_dwordx4 v158, v[84:87], s[100:101] offset:16
	global_store_dwordx4 v158, v[72:75], s[100:101] offset:512
	global_store_dwordx4 v158, v[68:71], s[100:101] offset:528
	v_add_u32_e32 v158, 0x80000, v240
	global_load_dwordx4 v[166:169], v158, s[100:101]
	global_load_dwordx4 v[170:173], v158, s[100:101] offset:16
	global_load_dwordx4 v[174:177], v158, s[100:101] offset:512
	global_load_dwordx4 v[178:181], v158, s[100:101] offset:528
	v_add_u32_e32 v158, 0x10000, v158
	global_load_dwordx4 v[182:185], v158, s[100:101]
	global_load_dwordx4 v[186:189], v158, s[100:101] offset:16
	global_load_dwordx4 v[190:193], v158, s[100:101] offset:512
	global_load_dwordx4 v[194:197], v158, s[100:101] offset:528
	v_add_u32_e32 v158, 0x10000, v158
	global_load_dwordx4 v[200:203], v158, s[100:101]
	global_load_dwordx4 v[204:207], v158, s[100:101] offset:16
	global_load_dwordx4 v[208:211], v158, s[100:101] offset:512
	global_load_dwordx4 v[212:215], v158, s[100:101] offset:528
	v_add_u32_e32 v158, 0x10000, v158
	global_load_dwordx4 v[216:219], v158, s[100:101]
	global_load_dwordx4 v[220:223], v158, s[100:101] offset:16
	global_load_dwordx4 v[224:227], v158, s[100:101] offset:512
	global_load_dwordx4 v[228:231], v158, s[100:101] offset:528
	global_load_dword v232, v241, s[98:99] offset:512
	global_load_dword v234, v241, s[98:99] offset:576
	global_load_dword v236, v241, s[98:99] offset:640
	global_load_dword v238, v241, s[98:99] offset:704
	s_waitcnt vmcnt(0)
	v_pk_fma_f32 v[64:65], v[64:65], v[232:233], v[166:167] op_sel_hi:[1,0,1]
	v_pk_fma_f32 v[66:67], v[66:67], v[232:233], v[168:169] op_sel_hi:[1,0,1]
	v_pk_fma_f32 v[60:61], v[60:61], v[232:233], v[170:171] op_sel_hi:[1,0,1]
	v_pk_fma_f32 v[62:63], v[62:63], v[232:233], v[172:173] op_sel_hi:[1,0,1]
	v_pk_fma_f32 v[52:53], v[52:53], v[232:233], v[174:175] op_sel_hi:[1,0,1]
	v_pk_fma_f32 v[54:55], v[54:55], v[232:233], v[176:177] op_sel_hi:[1,0,1]
	v_pk_fma_f32 v[44:45], v[44:45], v[232:233], v[178:179] op_sel_hi:[1,0,1]
	v_pk_fma_f32 v[46:47], v[46:47], v[232:233], v[180:181] op_sel_hi:[1,0,1]
	v_pk_fma_f32 v[56:57], v[56:57], v[234:235], v[182:183] op_sel_hi:[1,0,1]
	v_pk_fma_f32 v[58:59], v[58:59], v[234:235], v[184:185] op_sel_hi:[1,0,1]
	v_pk_fma_f32 v[48:49], v[48:49], v[234:235], v[186:187] op_sel_hi:[1,0,1]
	v_pk_fma_f32 v[50:51], v[50:51], v[234:235], v[188:189] op_sel_hi:[1,0,1]
	v_pk_fma_f32 v[36:37], v[36:37], v[234:235], v[190:191] op_sel_hi:[1,0,1]
	v_pk_fma_f32 v[38:39], v[38:39], v[234:235], v[192:193] op_sel_hi:[1,0,1]
	v_pk_fma_f32 v[28:29], v[28:29], v[234:235], v[194:195] op_sel_hi:[1,0,1]
	v_pk_fma_f32 v[30:31], v[30:31], v[234:235], v[196:197] op_sel_hi:[1,0,1]
	v_pk_fma_f32 v[40:41], v[40:41], v[236:237], v[200:201] op_sel_hi:[1,0,1]
	v_pk_fma_f32 v[42:43], v[42:43], v[236:237], v[202:203] op_sel_hi:[1,0,1]
	v_pk_fma_f32 v[32:33], v[32:33], v[236:237], v[204:205] op_sel_hi:[1,0,1]
	v_pk_fma_f32 v[34:35], v[34:35], v[236:237], v[206:207] op_sel_hi:[1,0,1]
	v_pk_fma_f32 v[20:21], v[20:21], v[236:237], v[208:209] op_sel_hi:[1,0,1]
	v_pk_fma_f32 v[22:23], v[22:23], v[236:237], v[210:211] op_sel_hi:[1,0,1]
	v_pk_fma_f32 v[12:13], v[12:13], v[236:237], v[212:213] op_sel_hi:[1,0,1]
	v_pk_fma_f32 v[14:15], v[14:15], v[236:237], v[214:215] op_sel_hi:[1,0,1]
	v_pk_fma_f32 v[24:25], v[24:25], v[238:239], v[216:217] op_sel_hi:[1,0,1]
	v_pk_fma_f32 v[26:27], v[26:27], v[238:239], v[218:219] op_sel_hi:[1,0,1]
	v_pk_fma_f32 v[16:17], v[16:17], v[238:239], v[220:221] op_sel_hi:[1,0,1]
	v_pk_fma_f32 v[18:19], v[18:19], v[238:239], v[222:223] op_sel_hi:[1,0,1]
	v_pk_fma_f32 v[8:9], v[8:9], v[238:239], v[224:225] op_sel_hi:[1,0,1]
	v_pk_fma_f32 v[10:11], v[10:11], v[238:239], v[226:227] op_sel_hi:[1,0,1]
	v_pk_fma_f32 v[4:5], v[4:5], v[238:239], v[228:229] op_sel_hi:[1,0,1]
	v_pk_fma_f32 v[6:7], v[6:7], v[238:239], v[230:231] op_sel_hi:[1,0,1]
	v_add_u32_e32 v158, 0x80000, v240
	global_store_dwordx4 v158, v[64:67], s[100:101]
	global_store_dwordx4 v158, v[60:63], s[100:101] offset:16
	global_store_dwordx4 v158, v[52:55], s[100:101] offset:512
	global_store_dwordx4 v158, v[44:47], s[100:101] offset:528
	v_add_u32_e32 v158, 0x10000, v158
	global_store_dwordx4 v158, v[56:59], s[100:101]
	global_store_dwordx4 v158, v[48:51], s[100:101] offset:16
	global_store_dwordx4 v158, v[36:39], s[100:101] offset:512
	global_store_dwordx4 v158, v[28:31], s[100:101] offset:528
	v_add_u32_e32 v158, 0x10000, v158
	global_store_dwordx4 v158, v[40:43], s[100:101]
	global_store_dwordx4 v158, v[32:35], s[100:101] offset:16
	global_store_dwordx4 v158, v[20:23], s[100:101] offset:512
	global_store_dwordx4 v158, v[12:15], s[100:101] offset:528
	v_add_u32_e32 v158, 0x10000, v158
	global_store_dwordx4 v158, v[24:27], s[100:101]
	global_store_dwordx4 v158, v[16:19], s[100:101] offset:16
	global_store_dwordx4 v158, v[8:11], s[100:101] offset:512
	global_store_dwordx4 v158, v[4:7], s[100:101] offset:528
	s_mov_b64 s[14:15], -1
	s_andn2_b64 vcc, exec, s[4:5]
	s_cbranch_vccnz .LBB0_1066
	s_andn2_b64 vcc, exec, s[6:7]
	s_cbranch_vccnz .LBB0_1065
	s_barrier
	s_branch .LBB0_1065
